# ring-base toggle instructions moved ahead of each step barrier (off the post-barrier critical path)
# speedup vs baseline: 1.0052x; 1.0028x over previous
.LBB0_400:
	v_cvt_pk_bf16_f32 v182, v148, v149
	v_cvt_pk_bf16_f32 v183, v152, v153
	v_cvt_pk_bf16_f32 v184, v154, v155
	v_cvt_pk_bf16_f32 v185, v158, v159
	v_cvt_pk_bf16_f32 v160, v150, v151
	v_cvt_pk_bf16_f32 v161, v156, v157
	v_cvt_pk_bf16_f32 v162, v162, v163
	v_cvt_pk_bf16_f32 v163, v166, v167
	s_cmpk_lt_u32 s51, 0x100
	s_cselect_b32 s0, s38, s34
	s_add_i32 s3, s0, s51
	s_mul_i32 s0, s3, 0x1800
	s_mul_hi_i32 s1, s3, 0x1800
	s_add_u32 s0, s39, s0
	s_addc_u32 s1, s42, s1
	s_max_i32 vcc_lo, s100, 0
	s_add_i32 vcc_lo, vcc_lo, s96
	s_add_i32 m0, vcc_lo, 0x4100
	s_nop 0
	global_load_lds_dwordx4 v129, s[0:1]
	s_add_i32 m0, vcc_lo, 0x4500
	s_nop 0
	global_load_lds_dwordx4 v130, s[0:1]
	s_mul_i32 s0, s3, 0x1800
	s_mul_hi_i32 s1, s3, 0x1800
	s_add_u32 s0, s28, s0
	s_addc_u32 s1, s29, s1
	s_max_i32 vcc_lo, s101, 0
	s_add_i32 vcc_lo, vcc_lo, s97
	s_add_i32 m0, vcc_lo, 0xa100
	s_nop 0
	global_load_lds_dwordx4 v128, s[0:1]
	ds_read_b64_tr_b16 v[186:187], v203 offset:0
	ds_read_b64_tr_b16 v[188:189], v203 offset:0x800
	ds_read_b64_tr_b16 v[214:215], v203 offset:0x200
	ds_read_b64_tr_b16 v[216:217], v203 offset:0xa00
	ds_read_b64_tr_b16 v[218:219], v203 offset:0x400
	ds_read_b64_tr_b16 v[220:221], v203 offset:0xc00
	ds_read_b64_tr_b16 v[222:223], v203 offset:0x600
	ds_read_b64_tr_b16 v[224:225], v203 offset:0xe00
	ds_read_b64_tr_b16 v[226:227], v203 offset:0x1000
	ds_read_b64_tr_b16 v[228:229], v203 offset:0x1800
	ds_read_b64_tr_b16 v[230:231], v203 offset:0x1200
	ds_read_b64_tr_b16 v[232:233], v203 offset:0x1a00
	ds_read_b64_tr_b16 v[234:235], v203 offset:0x1400
	ds_read_b64_tr_b16 v[236:237], v203 offset:0x1c00
	ds_read_b64_tr_b16 v[238:239], v203 offset:0x1600
	ds_read_b64_tr_b16 v[240:241], v203 offset:0x1e00
	s_nop 0
	s_waitcnt lgkmcnt(8)
	v_exp_f32_e32 v112, v112
	v_mfma_f32_32x32x16_bf16 v[0:15], v[144:147], v[186:189], v[0:15]
	v_exp_f32_e32 v113, v113
	v_exp_f32_e32 v114, v114
	v_exp_f32_e32 v115, v115
	v_exp_f32_e32 v116, v116
	v_exp_f32_e32 v117, v117
	v_exp_f32_e32 v118, v118
	v_exp_f32_e32 v119, v119
	v_mfma_f32_32x32x16_bf16 v[48:63], v[144:147], v[214:217], v[48:63]
	v_exp_f32_e32 v120, v120
	v_exp_f32_e32 v121, v121
	v_exp_f32_e32 v122, v122
	v_exp_f32_e32 v123, v123
	v_exp_f32_e32 v124, v124
	v_exp_f32_e32 v125, v125
	v_exp_f32_e32 v126, v126
	v_mfma_f32_32x32x16_bf16 v[32:47], v[144:147], v[218:221], v[32:47]
	v_exp_f32_e32 v127, v127
	v_mfma_f32_32x32x16_bf16 v[16:31], v[144:147], v[222:225], v[16:31]
	ds_read_b64_tr_b16 v[144:145], v203 offset:0x2000
	ds_read_b64_tr_b16 v[146:147], v203 offset:0x2800
	ds_read_b64_tr_b16 v[186:187], v203 offset:0x2200
	ds_read_b64_tr_b16 v[188:189], v203 offset:0x2a00
	ds_read_b64_tr_b16 v[214:215], v203 offset:0x2400
	ds_read_b64_tr_b16 v[216:217], v203 offset:0x2c00
	ds_read_b64_tr_b16 v[218:219], v203 offset:0x2600
	ds_read_b64_tr_b16 v[220:221], v203 offset:0x2e00
	s_waitcnt lgkmcnt(8)
	ds_read_b64_tr_b16 v[222:223], v203 offset:0x3000
	ds_read_b64_tr_b16 v[224:225], v203 offset:0x3800
	s_nop 0
	v_mfma_f32_32x32x16_bf16 v[0:15], v[140:143], v[226:229], v[0:15]
	ds_read_b64_tr_b16 v[226:227], v203 offset:0x3200
	ds_read_b64_tr_b16 v[228:229], v203 offset:0x3a00
	v_mfma_f32_32x32x16_bf16 v[48:63], v[140:143], v[230:233], v[48:63]
	ds_read_b64_tr_b16 v[230:231], v203 offset:0x3400
	ds_read_b64_tr_b16 v[232:233], v203 offset:0x3c00
	v_mfma_f32_32x32x16_bf16 v[32:47], v[140:143], v[234:237], v[32:47]
	ds_read_b64_tr_b16 v[234:235], v203 offset:0x3600
	ds_read_b64_tr_b16 v[236:237], v203 offset:0x3e00
	s_waitcnt lgkmcnt(8)
	s_nop 0
	s_waitcnt lgkmcnt(0)
	v_mfma_f32_32x32x16_bf16 v[16:31], v[140:143], v[238:241], v[16:31]
	v_add_f32_e32 v140, 0, v112
	v_add_f32_e32 v140, v113, v140
	v_add_f32_e32 v140, v114, v140
	v_add_f32_e32 v140, v115, v140
	v_add_f32_e32 v140, v116, v140
	v_add_f32_e32 v140, v117, v140
	v_add_f32_e32 v140, v118, v140
	v_mfma_f32_32x32x16_bf16 v[0:15], v[182:185], v[144:147], v[0:15]
	v_add_f32_e32 v140, v119, v140
	v_add_f32_e32 v140, v120, v140
	v_add_f32_e32 v140, v121, v140
	v_add_f32_e32 v140, v122, v140
	v_add_f32_e32 v140, v123, v140
	v_add_f32_e32 v140, v124, v140
	v_add_f32_e32 v140, v125, v140
	v_mfma_f32_32x32x16_bf16 v[48:63], v[182:185], v[186:189], v[48:63]
	v_add_f32_e32 v140, v126, v140
	v_add_f32_e32 v165, v127, v140
	v_cvt_pk_bf16_f32 v144, v112, v113
	v_cvt_pk_bf16_f32 v145, v114, v115
	v_cvt_pk_bf16_f32 v146, v116, v117
	v_cvt_pk_bf16_f32 v147, v118, v119
	v_cvt_pk_bf16_f32 v140, v120, v121
	v_mfma_f32_32x32x16_bf16 v[32:47], v[182:185], v[214:217], v[32:47]
	v_cvt_pk_bf16_f32 v141, v122, v123
	v_cvt_pk_bf16_f32 v142, v124, v125
	v_cvt_pk_bf16_f32 v143, v126, v127
	v_mfma_f32_32x32x16_bf16 v[16:31], v[182:185], v[218:221], v[16:31]
	v_add_u32_e32 v208, s101, v208
	v_add_u32_e32 v209, s101, v209
	v_add_u32_e32 v210, s101, v210
	v_add_u32_e32 v211, s101, v211
	s_waitcnt vmcnt(3)
	s_waitcnt lgkmcnt(0)
	s_barrier
	v_mfma_f32_32x32x16_bf16 v[0:15], v[160:163], v[222:225], v[0:15]
	v_mfma_f32_32x32x16_bf16 v[48:63], v[160:163], v[226:229], v[48:63]
	v_mfma_f32_32x32x16_bf16 v[32:47], v[160:163], v[230:233], v[32:47]
	v_mfma_f32_32x32x16_bf16 v[16:31], v[160:163], v[234:237], v[16:31]
	ds_read_b128 v[160:163], v208 offset:32768
	ds_read_b128 v[222:225], v208 offset:36864
	v_exp_f32_e32 v166, v84
	v_exp_f32_e32 v167, v85
	s_waitcnt lgkmcnt(1)
	v_mfma_f32_32x32x16_bf16 v[112:127], v[160:163], v[64:67], v[96:111]
	ds_read_b128 v[160:163], v209 offset:32768
	ds_read_b128 v[226:229], v209 offset:36864
	ds_read_b128 v[238:241], v210 offset:36864
	ds_read_b128 v[182:185], v210 offset:32768
	ds_read_b128 v[242:245], v211 offset:36864
	ds_read_b128 v[188:191], v211 offset:32768
	v_exp_f32_e32 v186, v90
	v_exp_f32_e32 v187, v91
	s_andn2_b64 s[0:1], s[6:7], exec
	s_and_b64 s[6:7], s[8:9], exec
	s_or_b64 s[6:7], s[0:1], s[6:7]
	s_waitcnt lgkmcnt(5)
	v_mfma_f32_32x32x16_bf16 v[112:127], v[160:163], v[68:71], v[112:127]
	v_exp_f32_e32 v160, v80
	v_exp_f32_e32 v161, v81
	v_exp_f32_e32 v162, v82
	v_exp_f32_e32 v163, v83
	v_add_f32_e32 v80, v160, v165
	v_add_f32_e32 v80, v161, v80
	v_add_f32_e32 v165, v162, v80
	s_waitcnt lgkmcnt(2)
	v_mfma_f32_32x32x16_bf16 v[112:127], v[182:185], v[72:75], v[112:127]
	v_exp_f32_e32 v182, v86
	v_exp_f32_e32 v183, v87
	v_exp_f32_e32 v184, v88
	v_exp_f32_e32 v185, v89
	v_add_f32_e32 v165, v163, v165
	v_add_f32_e32 v165, v166, v165
	v_add_f32_e32 v165, v167, v165
	s_waitcnt lgkmcnt(0)
	v_mfma_f32_32x32x16_bf16 v[112:127], v[188:191], v[76:79], v[112:127]
	v_exp_f32_e32 v188, v92
	v_exp_f32_e32 v189, v93
	v_exp_f32_e32 v190, v94
	v_exp_f32_e32 v191, v95
	v_add_f32_e32 v165, v182, v165
	v_add_f32_e32 v165, v183, v165
	v_add_f32_e32 v165, v184, v165
	v_mfma_f32_32x32x16_bf16 v[80:95], v[222:225], v[64:67], v[96:111]
	v_add_f32_e32 v165, v185, v165
	v_add_f32_e32 v165, v186, v165
	v_add_f32_e32 v165, v187, v165
	v_add_f32_e32 v165, v188, v165
	v_add_f32_e32 v165, v189, v165
	v_add_f32_e32 v165, v190, v165
	v_add_f32_e32 v165, v191, v165
	v_mfma_f32_32x32x16_bf16 v[80:95], v[226:229], v[68:71], v[80:95]
	v_mov_b32_e32 v179, v165
	s_nop 1
	v_permlane32_swap_b32_e32 v165, v179
	v_add_f32_e64 v178, v164, v178
	v_add_f32_e64 v179, v165, v179
	v_cmp_ge_f32_e32 vcc, s99, v179
	s_cmp_eq_u64 vcc, exec
	v_mfma_f32_32x32x16_bf16 v[80:95], v[238:241], v[72:75], v[80:95]
	v_mfma_f32_32x32x16_bf16 v[80:95], v[242:245], v[76:79], v[80:95]
	s_cbranch_scc0 .LBB0_408

.LBB0_403:
	v_add_f32_e32 v178, v179, v178
	ds_read_b64_tr_b16 v[182:183], v202 offset:0
	ds_read_b64_tr_b16 v[184:185], v202 offset:0x800
	ds_read_b64_tr_b16 v[186:187], v202 offset:0x200
	ds_read_b64_tr_b16 v[188:189], v202 offset:0xa00
	ds_read_b64_tr_b16 v[214:215], v202 offset:0x400
	ds_read_b64_tr_b16 v[216:217], v202 offset:0xc00
	ds_read_b64_tr_b16 v[218:219], v202 offset:0x600
	ds_read_b64_tr_b16 v[220:221], v202 offset:0xe00
	ds_read_b64_tr_b16 v[222:223], v202 offset:0x1000
	ds_read_b64_tr_b16 v[224:225], v202 offset:0x1800
	ds_read_b64_tr_b16 v[226:227], v202 offset:0x1200
	ds_read_b64_tr_b16 v[228:229], v202 offset:0x1a00
	ds_read_b64_tr_b16 v[230:231], v202 offset:0x1400
	ds_read_b64_tr_b16 v[232:233], v202 offset:0x1c00
	ds_read_b64_tr_b16 v[234:235], v202 offset:0x1600
	ds_read_b64_tr_b16 v[236:237], v202 offset:0x1e00
	s_nop 0
	s_waitcnt lgkmcnt(8)
	v_exp_f32_e32 v112, v112
	v_mfma_f32_32x32x16_bf16 v[0:15], v[144:147], v[182:185], v[0:15]
	v_exp_f32_e32 v113, v113
	v_exp_f32_e32 v114, v114
	v_exp_f32_e32 v115, v115
	v_exp_f32_e32 v116, v116
	v_exp_f32_e32 v117, v117
	v_exp_f32_e32 v118, v118
	v_exp_f32_e32 v119, v119
	v_mfma_f32_32x32x16_bf16 v[48:63], v[144:147], v[186:189], v[48:63]
	v_exp_f32_e32 v120, v120
	v_exp_f32_e32 v121, v121
	v_exp_f32_e32 v122, v122
	v_exp_f32_e32 v123, v123
	v_exp_f32_e32 v124, v124
	v_exp_f32_e32 v125, v125
	v_exp_f32_e32 v126, v126
	v_mfma_f32_32x32x16_bf16 v[32:47], v[144:147], v[214:217], v[32:47]
	v_exp_f32_e32 v127, v127
	s_addk_i32 s51, 0x80
	s_add_i32 s50, s50, 2
	s_and_b64 vcc, exec, s[8:9]
	v_mfma_f32_32x32x16_bf16 v[16:31], v[144:147], v[218:221], v[16:31]
	ds_read_b64_tr_b16 v[144:145], v202 offset:0x2000
	ds_read_b64_tr_b16 v[146:147], v202 offset:0x2800
	ds_read_b64_tr_b16 v[182:183], v202 offset:0x2200
	ds_read_b64_tr_b16 v[184:185], v202 offset:0x2a00
	ds_read_b64_tr_b16 v[186:187], v202 offset:0x2400
	ds_read_b64_tr_b16 v[188:189], v202 offset:0x2c00
	ds_read_b64_tr_b16 v[214:215], v202 offset:0x2600
	ds_read_b64_tr_b16 v[216:217], v202 offset:0x2e00
	s_waitcnt lgkmcnt(8)
	ds_read_b64_tr_b16 v[218:219], v202 offset:0x3000
	ds_read_b64_tr_b16 v[220:221], v202 offset:0x3800
	s_nop 0
	v_mfma_f32_32x32x16_bf16 v[0:15], v[140:143], v[222:225], v[0:15]
	ds_read_b64_tr_b16 v[222:223], v202 offset:0x3200
	ds_read_b64_tr_b16 v[224:225], v202 offset:0x3a00
	v_mfma_f32_32x32x16_bf16 v[48:63], v[140:143], v[226:229], v[48:63]
	ds_read_b64_tr_b16 v[226:227], v202 offset:0x3400
	ds_read_b64_tr_b16 v[228:229], v202 offset:0x3c00
	v_mfma_f32_32x32x16_bf16 v[32:47], v[140:143], v[230:233], v[32:47]
	ds_read_b64_tr_b16 v[230:231], v202 offset:0x3600
	ds_read_b64_tr_b16 v[232:233], v202 offset:0x3e00
	s_waitcnt lgkmcnt(8)
	s_nop 0
	s_waitcnt lgkmcnt(0)
	v_mfma_f32_32x32x16_bf16 v[16:31], v[140:143], v[234:237], v[16:31]
	v_add_f32_e32 v140, 0, v112
	v_add_f32_e32 v140, v113, v140
	v_add_f32_e32 v140, v114, v140
	v_add_f32_e32 v140, v115, v140
	v_add_f32_e32 v140, v116, v140
	v_add_f32_e32 v140, v117, v140
	v_add_f32_e32 v140, v118, v140
	v_mfma_f32_32x32x16_bf16 v[0:15], v[164:167], v[144:147], v[0:15]
	v_add_f32_e32 v140, v119, v140
	v_add_f32_e32 v140, v120, v140
	v_add_f32_e32 v140, v121, v140
	v_add_f32_e32 v140, v122, v140
	v_add_f32_e32 v140, v123, v140
	v_add_f32_e32 v140, v124, v140
	v_add_f32_e32 v140, v125, v140
	v_mfma_f32_32x32x16_bf16 v[48:63], v[164:167], v[182:185], v[48:63]
	v_add_f32_e32 v140, v126, v140
	v_cvt_pk_bf16_f32 v144, v112, v113
	v_cvt_pk_bf16_f32 v145, v114, v115
	v_cvt_pk_bf16_f32 v146, v116, v117
	v_cvt_pk_bf16_f32 v147, v118, v119
	v_mfma_f32_32x32x16_bf16 v[32:47], v[164:167], v[186:189], v[32:47]
	v_mfma_f32_32x32x16_bf16 v[16:31], v[164:167], v[214:217], v[16:31]
	v_add_f32_e32 v164, v127, v140
	v_cvt_pk_bf16_f32 v140, v120, v121
	v_cvt_pk_bf16_f32 v141, v122, v123
	v_cvt_pk_bf16_f32 v142, v124, v125
	v_cvt_pk_bf16_f32 v143, v126, v127
	v_mfma_f32_32x32x16_bf16 v[0:15], v[160:163], v[218:221], v[0:15]
	v_add_u32_e32 v202, s100, v202
	v_add_u32_e32 v203, s100, v203
	s_sub_i32 s100, 0, s100
	s_sub_i32 s101, 0, s101
	s_waitcnt vmcnt(3)
	s_cbranch_vccz .Ldma_w3
	s_waitcnt vmcnt(0)
.Ldma_w3:
	s_waitcnt lgkmcnt(0)
	s_barrier
	v_mfma_f32_32x32x16_bf16 v[48:63], v[160:163], v[222:225], v[48:63]
	v_mfma_f32_32x32x16_bf16 v[32:47], v[160:163], v[226:229], v[32:47]
	v_mfma_f32_32x32x16_bf16 v[16:31], v[160:163], v[230:233], v[16:31]
	s_cbranch_vccnz .LBB0_411
	s_mov_b64 s[8:9], s[6:7]
	s_branch .LBB0_398
